# HGRN2 chain consumer loop hand-pipelined: LDS reads issued ~10 ahead via register ring + counted lgkmcnt, MFMA results consumed with lag (no s_nop)
# baseline (speedup 1.0000x reference)
.LBB0_1004:
	s_bitcmp1_b32 s0, 0
	s_cselect_b32 s1, 0x10400, 0
	v_add_u32_e32 v16, s1, v38
	v_lshl_add_u32 v69, v39, 2, s1
	v_add_u32_e32 v68, v16, v37
	v_add_u32_e32 v71, v16, v41
	v_add_u32_e32 v70, v16, v42
	v_add_u32_e32 v72, v16, v40
	ds_read_b128 v[44:47], v68 offset:45056
	ds_read_b128 v[48:51], v68 offset:45120
	ds_read_b128 v[80:83], v69 offset:63488
	ds_read_b128 v[84:87], v69 offset:63552
	ds_read_b128 v[88:91], v69 offset:63616
	ds_read_b128 v[92:95], v69 offset:63680
	ds_read_b128 v[96:99], v69 offset:63744
	ds_read_b128 v[100:103], v69 offset:63808
	ds_read_b128 v[104:107], v69 offset:63872
	ds_read_b128 v[108:111], v69 offset:63936
	ds_read_b128 v[112:115], v71 offset:17408
	ds_read_b128 v[116:119], v70 offset:0
	ds_read_b128 v[120:123], v70 offset:64
	s_waitcnt lgkmcnt(10)
	v_pk_mul_f32 v[82:83], v[34:35], v[82:83]
	v_pk_mul_f32 v[80:81], v[32:33], v[80:81]
	ds_read_b128 v[124:127], v70 offset:128
	s_waitcnt lgkmcnt(10)
	v_pk_mul_f32 v[86:87], v[30:31], v[86:87]
	v_pk_mul_f32 v[84:85], v[28:29], v[84:85]
	v_cvt_pk_bf16_f32 v52, v80, v81
	v_cvt_pk_bf16_f32 v53, v82, v83
	v_cvt_pk_bf16_f32 v54, v84, v85
	v_cvt_pk_bf16_f32 v55, v86, v87
	ds_read_b128 v[128:131], v70 offset:192
	ds_read_b128 v[132:135], v71 offset:19712
	ds_read_b128 v[136:139], v70 offset:4352
	ds_read_b128 v[140:143], v70 offset:4416
	ds_read_b128 v[80:83], v70 offset:4480
	ds_read_b128 v[84:87], v70 offset:4544
	s_waitcnt lgkmcnt(9)
	v_mfma_f32_16x16x32_bf16 v[76:79], v[112:115], v[44:47], 0
	ds_read_b128 v[112:115], v71 offset:22016
	v_pk_mul_f32 v[90:91], v[26:27], v[90:91]
	v_pk_mul_f32 v[88:89], v[24:25], v[88:89]
	v_pk_mul_f32 v[94:95], v[22:23], v[94:95]
	v_pk_mul_f32 v[92:93], v[20:21], v[92:93]
	v_cvt_pk_bf16_f32 v56, v88, v89
	v_cvt_pk_bf16_f32 v57, v90, v91
	v_cvt_pk_bf16_f32 v58, v92, v93
	v_cvt_pk_bf16_f32 v59, v94, v95
	ds_read_b128 v[88:91], v71 offset:22080
	s_waitcnt lgkmcnt(10)
	v_mfma_f32_16x16x32_bf16 v[76:79], v[116:119], v[52:55], v[76:79]
	v_pk_mul_f32 v[98:99], v[18:19], v[98:99]
	v_pk_mul_f32 v[96:97], v[14:15], v[96:97]
	v_pk_mul_f32 v[102:103], v[12:13], v[102:103]
	v_pk_mul_f32 v[100:101], v[10:11], v[100:101]
	v_cvt_pk_bf16_f32 v60, v96, v97
	v_cvt_pk_bf16_f32 v61, v98, v99
	v_cvt_pk_bf16_f32 v62, v100, v101
	v_cvt_pk_bf16_f32 v63, v102, v103
	ds_read_b128 v[92:95], v70 offset:8704
	s_waitcnt lgkmcnt(10)
	v_mfma_f32_16x16x32_bf16 v[76:79], v[120:123], v[56:59], v[76:79]
	v_pk_mul_f32 v[106:107], v[8:9], v[106:107]
	v_pk_mul_f32 v[104:105], v[6:7], v[104:105]
	v_pk_mul_f32 v[110:111], v[4:5], v[110:111]
	v_pk_mul_f32 v[108:109], v[2:3], v[108:109]
	v_cvt_pk_bf16_f32 v64, v104, v105
	v_cvt_pk_bf16_f32 v65, v106, v107
	v_cvt_pk_bf16_f32 v66, v108, v109
	v_cvt_pk_bf16_f32 v67, v110, v111
	ds_read_b128 v[116:119], v70 offset:8768
	s_waitcnt lgkmcnt(10)
	v_mfma_f32_16x16x32_bf16 v[76:79], v[124:127], v[60:63], v[76:79]
	ds_read_b128 v[96:99], v70 offset:8832
	s_waitcnt lgkmcnt(10)
	v_mfma_f32_16x16x32_bf16 v[76:79], v[128:131], v[64:67], v[76:79]
	ds_read_b128 v[100:103], v70 offset:8896
	s_waitcnt lgkmcnt(10)
	v_mfma_f32_16x16x32_bf16 v[144:147], v[132:135], v[44:47], 0
	ds_read_b128 v[120:123], v71 offset:24320
	s_waitcnt lgkmcnt(10)
	v_mfma_f32_16x16x32_bf16 v[144:147], v[136:139], v[52:55], v[144:147]
	ds_read_b128 v[104:107], v71 offset:24384
	s_waitcnt lgkmcnt(10)
	v_mfma_f32_16x16x32_bf16 v[144:147], v[140:143], v[56:59], v[144:147]
	ds_read_b128 v[108:111], v72 offset:0
	s_waitcnt lgkmcnt(10)
	v_mfma_f32_16x16x32_bf16 v[144:147], v[80:83], v[60:63], v[144:147]
	ds_read_b128 v[124:127], v72 offset:64
	s_waitcnt lgkmcnt(10)
	v_mfma_f32_16x16x32_bf16 v[144:147], v[84:87], v[64:67], v[144:147]
	v_cvt_pk_bf16_f32 v148, v76, v77
	v_cvt_pk_bf16_f32 v149, v78, v79
	global_store_dwordx2 v[0:1], v[148:149], off offset:-64
	ds_read_b128 v[128:131], v72 offset:128
	s_waitcnt lgkmcnt(10)
	v_mfma_f32_16x16x32_bf16 v[76:79], v[112:115], v[44:47], 0
	ds_read_b128 v[132:135], v72 offset:192
	s_waitcnt lgkmcnt(10)
	v_mfma_f32_16x16x32_bf16 v[76:79], v[88:91], v[48:51], v[76:79]
	ds_read_b128 v[136:139], v71 offset:26624
	s_waitcnt lgkmcnt(10)
	v_mfma_f32_16x16x32_bf16 v[76:79], v[92:95], v[52:55], v[76:79]
	ds_read_b128 v[140:143], v71 offset:26688
	s_waitcnt lgkmcnt(10)
	v_mfma_f32_16x16x32_bf16 v[76:79], v[116:119], v[56:59], v[76:79]
	ds_read_b128 v[80:83], v16 offset:64512
	s_waitcnt lgkmcnt(10)
	v_mfma_f32_16x16x32_bf16 v[76:79], v[96:99], v[60:63], v[76:79]
	ds_read_b128 v[84:87], v16 offset:64000
	s_waitcnt lgkmcnt(10)
	v_mfma_f32_16x16x32_bf16 v[76:79], v[100:103], v[64:67], v[76:79]
	v_cvt_pk_bf16_f32 v150, v144, v145
	v_cvt_pk_bf16_f32 v151, v146, v147
	global_store_dwordx2 v[0:1], v[150:151], off offset:-32
	ds_read_b128 v[112:115], v71 offset:28928
	s_waitcnt lgkmcnt(10)
	v_mfma_f32_16x16x32_bf16 v[144:147], v[120:123], v[44:47], 0
	ds_read_b128 v[88:91], v71 offset:28992
	s_waitcnt lgkmcnt(10)
	v_mfma_f32_16x16x32_bf16 v[144:147], v[104:107], v[48:51], v[144:147]
	ds_read_b128 v[92:95], v16 offset:64576
	s_waitcnt lgkmcnt(10)
	v_mfma_f32_16x16x32_bf16 v[144:147], v[108:111], v[52:55], v[144:147]
	ds_read_b128 v[116:119], v16 offset:64064
	s_waitcnt lgkmcnt(10)
	v_mfma_f32_16x16x32_bf16 v[144:147], v[124:127], v[56:59], v[144:147]
	ds_read_b128 v[96:99], v71 offset:31232
	s_waitcnt lgkmcnt(10)
	v_mfma_f32_16x16x32_bf16 v[144:147], v[128:131], v[60:63], v[144:147]
	ds_read_b128 v[100:103], v71 offset:31296
	s_waitcnt lgkmcnt(10)
	v_mfma_f32_16x16x32_bf16 v[144:147], v[132:135], v[64:67], v[144:147]
	v_cvt_pk_bf16_f32 v152, v76, v77
	v_cvt_pk_bf16_f32 v153, v78, v79
	global_store_dwordx2 v[0:1], v[152:153], off
	ds_read_b128 v[120:123], v16 offset:64640
	s_waitcnt lgkmcnt(10)
	v_mfma_f32_16x16x32_bf16 v[156:159], v[136:139], v[44:47], 0
	ds_read_b128 v[104:107], v16 offset:64128
	s_waitcnt lgkmcnt(10)
	v_mfma_f32_16x16x32_bf16 v[156:159], v[140:143], v[48:51], v[156:159]
	ds_read_b128 v[108:111], v71 offset:33536
	ds_read_b128 v[124:127], v71 offset:33600
	ds_read_b128 v[128:131], v16 offset:64704
	s_waitcnt lgkmcnt(10)
	v_mfma_f32_16x16x32_bf16 v[160:163], v[112:115], v[44:47], 0
	ds_read_b128 v[132:135], v16 offset:64192
	s_waitcnt lgkmcnt(10)
	v_mfma_f32_16x16x32_bf16 v[160:163], v[88:91], v[48:51], v[160:163]
	v_cvt_pk_bf16_f32 v154, v144, v145
	v_cvt_pk_bf16_f32 v155, v146, v147
	global_store_dwordx2 v[0:1], v[154:155], off offset:32
	v_lshl_add_u64 v[0:1], v[0:1], 0, s[36:37]
	ds_read_b128 v[136:139], v71 offset:35840
	ds_read_b128 v[140:143], v71 offset:35904
	ds_read_b128 v[112:115], v16 offset:64768
	s_waitcnt lgkmcnt(10)
	v_mfma_f32_16x16x32_bf16 v[164:167], v[96:99], v[44:47], 0
	ds_read_b128 v[88:91], v16 offset:64256
	s_waitcnt lgkmcnt(10)
	v_mfma_f32_16x16x32_bf16 v[164:167], v[100:103], v[48:51], v[164:167]
	v_pk_mul_f32 v[86:87], v[158:159], v[86:87]
	v_pk_mul_f32 v[84:85], v[156:157], v[84:85]
	v_pk_fma_f32 v[34:35], v[34:35], v[82:83], v[86:87]
	v_pk_fma_f32 v[32:33], v[32:33], v[80:81], v[84:85]
	ds_read_b128 v[96:99], v71 offset:38144
	ds_read_b128 v[100:103], v71 offset:38208
	ds_read_b128 v[80:83], v16 offset:64832
	s_waitcnt lgkmcnt(10)
	v_mfma_f32_16x16x32_bf16 v[156:159], v[108:111], v[44:47], 0
	ds_read_b128 v[84:87], v16 offset:64320
	s_waitcnt lgkmcnt(10)
	v_mfma_f32_16x16x32_bf16 v[156:159], v[124:127], v[48:51], v[156:159]
	v_pk_mul_f32 v[118:119], v[162:163], v[118:119]
	v_pk_mul_f32 v[116:117], v[160:161], v[116:117]
	v_pk_fma_f32 v[30:31], v[30:31], v[94:95], v[118:119]
	v_pk_fma_f32 v[28:29], v[28:29], v[92:93], v[116:117]
	ds_read_b128 v[108:111], v71 offset:40448
	ds_read_b128 v[124:127], v71 offset:40512
	ds_read_b128 v[92:95], v16 offset:64896
	s_waitcnt lgkmcnt(10)
	v_mfma_f32_16x16x32_bf16 v[160:163], v[136:139], v[44:47], 0
	ds_read_b128 v[116:119], v16 offset:64384
	s_waitcnt lgkmcnt(10)
	v_mfma_f32_16x16x32_bf16 v[160:163], v[140:143], v[48:51], v[160:163]
	v_pk_mul_f32 v[106:107], v[166:167], v[106:107]
	v_pk_mul_f32 v[104:105], v[164:165], v[104:105]
	v_pk_fma_f32 v[26:27], v[26:27], v[122:123], v[106:107]
	v_pk_fma_f32 v[24:25], v[24:25], v[120:121], v[104:105]
	ds_read_b128 v[136:139], v71 offset:42752
	ds_read_b128 v[140:143], v71 offset:42816
	ds_read_b128 v[120:123], v16 offset:64960
	s_waitcnt lgkmcnt(10)
	v_mfma_f32_16x16x32_bf16 v[164:167], v[96:99], v[44:47], 0
	ds_read_b128 v[104:107], v16 offset:64448
	s_waitcnt lgkmcnt(10)
	v_mfma_f32_16x16x32_bf16 v[164:167], v[100:103], v[48:51], v[164:167]
	v_pk_mul_f32 v[134:135], v[158:159], v[134:135]
	v_pk_mul_f32 v[132:133], v[156:157], v[132:133]
	v_pk_fma_f32 v[22:23], v[22:23], v[130:131], v[134:135]
	v_pk_fma_f32 v[20:21], v[20:21], v[128:129], v[132:133]
	s_waitcnt lgkmcnt(7)
	v_mfma_f32_16x16x32_bf16 v[156:159], v[108:111], v[44:47], 0
	s_waitcnt lgkmcnt(6)
	v_mfma_f32_16x16x32_bf16 v[156:159], v[124:127], v[48:51], v[156:159]
	v_pk_mul_f32 v[90:91], v[162:163], v[90:91]
	v_pk_mul_f32 v[88:89], v[160:161], v[88:89]
	v_pk_fma_f32 v[18:19], v[18:19], v[114:115], v[90:91]
	v_pk_fma_f32 v[14:15], v[14:15], v[112:113], v[88:89]
	s_waitcnt lgkmcnt(3)
	v_mfma_f32_16x16x32_bf16 v[160:163], v[136:139], v[44:47], 0
	s_waitcnt lgkmcnt(2)
	v_mfma_f32_16x16x32_bf16 v[160:163], v[140:143], v[48:51], v[160:163]
	v_pk_mul_f32 v[86:87], v[166:167], v[86:87]
	v_pk_mul_f32 v[84:85], v[164:165], v[84:85]
	v_pk_fma_f32 v[12:13], v[12:13], v[82:83], v[86:87]
	v_pk_fma_f32 v[10:11], v[10:11], v[80:81], v[84:85]
	v_pk_mul_f32 v[118:119], v[158:159], v[118:119]
	v_pk_mul_f32 v[116:117], v[156:157], v[116:117]
	v_pk_fma_f32 v[8:9], v[8:9], v[94:95], v[118:119]
	v_pk_fma_f32 v[6:7], v[6:7], v[92:93], v[116:117]
	s_waitcnt lgkmcnt(0)
	s_barrier
	v_pk_mul_f32 v[106:107], v[162:163], v[106:107]
	v_pk_mul_f32 v[104:105], v[160:161], v[104:105]
	v_pk_fma_f32 v[4:5], v[4:5], v[122:123], v[106:107]
	v_pk_fma_f32 v[2:3], v[2:3], v[120:121], v[104:105]
	s_add_i32 s0, s0, 1
	s_cmp_eq_u32 s0, 64
	s_cbranch_scc0 .LBB0_1004
	s_mov_b64 s[0:1], 0
